# v69: calmer barrier polling (s_sleep 6 between polls instead of 1)
# speedup vs baseline: 1.0024x; 1.0024x over previous
.LBB0_97:
	global_load_dword v16, v17, s[6:7] sc1
	global_load_dword v1, v17, s[8:9] sc1
	global_load_dword v2, v17, s[10:11] sc1
	global_load_dword v3, v17, s[12:13] sc1
	global_load_dword v4, v17, s[14:15] sc1
	global_load_dword v5, v17, s[16:17] sc1
	global_load_dword v6, v17, s[18:19] sc1
	global_load_dword v7, v17, s[20:21] sc1
	global_load_dword v8, v17, s[22:23] sc1
	global_load_dword v9, v17, s[24:25] sc1
	global_load_dword v10, v17, s[26:27] sc1
	global_load_dword v11, v17, s[28:29] sc1
	global_load_dword v12, v17, s[30:31] sc1
	global_load_dword v13, v17, s[34:35] sc1
	global_load_dword v14, v17, s[36:37] sc1
	global_load_dword v15, v17, s[38:39] sc1
	s_mov_b64 s[40:41], -1
	s_mov_b64 s[42:43], -1
	s_waitcnt vmcnt(14)
	v_add_u32_e32 v18, v1, v16
	s_waitcnt vmcnt(13)
	v_add_u32_e32 v18, v18, v2
	s_waitcnt vmcnt(12)
	v_add_u32_e32 v18, v18, v3
	s_waitcnt vmcnt(11)
	v_add_u32_e32 v18, v18, v4
	s_waitcnt vmcnt(10)
	v_add_u32_e32 v18, v18, v5
	s_waitcnt vmcnt(9)
	v_add_u32_e32 v18, v18, v6
	s_waitcnt vmcnt(8)
	v_add_u32_e32 v18, v18, v7
	s_waitcnt vmcnt(7)
	v_add_u32_e32 v18, v18, v8
	s_waitcnt vmcnt(6)
	v_add_u32_e32 v18, v18, v9
	s_waitcnt vmcnt(5)
	v_add_u32_e32 v18, v18, v10
	s_waitcnt vmcnt(4)
	v_add_u32_e32 v18, v18, v11
	s_waitcnt vmcnt(3)
	v_add_u32_e32 v18, v18, v12
	s_waitcnt vmcnt(2)
	v_add_u32_e32 v18, v18, v13
	s_waitcnt vmcnt(1)
	v_add_u32_e32 v18, v18, v14
	s_waitcnt vmcnt(0)
	v_add_u32_e32 v18, v18, v15
	v_cmp_eq_u32_e32 vcc, s33, v18
	s_cbranch_vccnz .LBB0_96
	s_and_b32 s40, s46, 0xff
	s_cmp_eq_u32 s40, 0
	s_mov_b64 s[40:41], -1
	s_mov_b64 s[44:45], -1
	s_sleep 6
	s_cbranch_scc1 .LBB0_101
	s_and_b64 vcc, exec, s[44:45]
	s_cbranch_vccz .LBB0_96

.LBB0_115:
	s_and_b32 s20, s24, 0xff
	s_mov_b64 s[18:19], -1
	s_cmp_lg_u32 s20, 0
	s_mov_b64 s[22:23], -1
	s_sleep 6
	s_cbranch_scc0 .LBB0_118
	s_and_b64 vcc, exec, s[22:23]
	s_cbranch_vccz .LBB0_114

.LBB0_132:
	s_and_b32 s18, s24, 0xff
	s_cmp_lg_u32 s18, 0
	s_mov_b64 s[20:21], -1
	s_sleep 6
	s_cbranch_scc0 .LBB0_135
	s_mov_b64 s[22:23], -1
	s_and_b64 vcc, exec, s[20:21]
	s_cbranch_vccz .LBB0_131

.LBB0_580:
	global_load_dword v16, v17, s[4:5] sc1
	global_load_dword v1, v17, s[6:7] sc1
	global_load_dword v2, v17, s[8:9] sc1
	global_load_dword v3, v17, s[10:11] sc1
	global_load_dword v4, v17, s[12:13] sc1
	global_load_dword v5, v17, s[14:15] sc1
	global_load_dword v6, v17, s[18:19] sc1
	global_load_dword v7, v17, s[20:21] sc1
	global_load_dword v8, v17, s[22:23] sc1
	global_load_dword v9, v17, s[24:25] sc1
	global_load_dword v10, v17, s[26:27] sc1
	global_load_dword v11, v17, s[28:29] sc1
	global_load_dword v12, v17, s[30:31] sc1
	global_load_dword v13, v17, s[34:35] sc1
	global_load_dword v14, v17, s[36:37] sc1
	global_load_dword v15, v17, s[38:39] sc1
	s_mov_b64 s[40:41], -1
	s_mov_b64 s[42:43], -1
	s_waitcnt vmcnt(14)
	v_add_u32_e32 v18, v1, v16
	s_waitcnt vmcnt(13)
	v_add_u32_e32 v18, v18, v2
	s_waitcnt vmcnt(12)
	v_add_u32_e32 v18, v18, v3
	s_waitcnt vmcnt(11)
	v_add_u32_e32 v18, v18, v4
	s_waitcnt vmcnt(10)
	v_add_u32_e32 v18, v18, v5
	s_waitcnt vmcnt(9)
	v_add_u32_e32 v18, v18, v6
	s_waitcnt vmcnt(8)
	v_add_u32_e32 v18, v18, v7
	s_waitcnt vmcnt(7)
	v_add_u32_e32 v18, v18, v8
	s_waitcnt vmcnt(6)
	v_add_u32_e32 v18, v18, v9
	s_waitcnt vmcnt(5)
	v_add_u32_e32 v18, v18, v10
	s_waitcnt vmcnt(4)
	v_add_u32_e32 v18, v18, v11
	s_waitcnt vmcnt(3)
	v_add_u32_e32 v18, v18, v12
	s_waitcnt vmcnt(2)
	v_add_u32_e32 v18, v18, v13
	s_waitcnt vmcnt(1)
	v_add_u32_e32 v18, v18, v14
	s_waitcnt vmcnt(0)
	v_add_u32_e32 v18, v18, v15
	v_cmp_eq_u32_e32 vcc, s33, v18
	s_cbranch_vccnz .LBB0_579
	s_and_b32 s40, s46, 0xff
	s_cmp_eq_u32 s40, 0
	s_mov_b64 s[40:41], -1
	s_mov_b64 s[44:45], -1
	s_sleep 6
	s_cbranch_scc1 .LBB0_584
	s_and_b64 vcc, exec, s[44:45]
	s_cbranch_vccz .LBB0_579

.LBB0_1217:
	global_load_dword v16, v17, s[4:5] sc1
	global_load_dword v1, v17, s[6:7] sc1
	global_load_dword v2, v17, s[8:9] sc1
	global_load_dword v3, v17, s[10:11] sc1
	global_load_dword v4, v17, s[12:13] sc1
	global_load_dword v5, v17, s[14:15] sc1
	global_load_dword v6, v17, s[16:17] sc1
	global_load_dword v7, v17, s[18:19] sc1
	global_load_dword v8, v17, s[20:21] sc1
	global_load_dword v9, v17, s[22:23] sc1
	global_load_dword v10, v17, s[24:25] sc1
	global_load_dword v11, v17, s[26:27] sc1
	global_load_dword v12, v17, s[28:29] sc1
	global_load_dword v13, v17, s[30:31] sc1
	global_load_dword v14, v17, s[34:35] sc1
	global_load_dword v15, v17, s[36:37] sc1
	s_mov_b64 s[38:39], -1
	s_mov_b64 s[40:41], -1
	s_waitcnt vmcnt(14)
	v_add_u32_e32 v18, v1, v16
	s_waitcnt vmcnt(13)
	v_add_u32_e32 v18, v18, v2
	s_waitcnt vmcnt(12)
	v_add_u32_e32 v18, v18, v3
	s_waitcnt vmcnt(11)
	v_add_u32_e32 v18, v18, v4
	s_waitcnt vmcnt(10)
	v_add_u32_e32 v18, v18, v5
	s_waitcnt vmcnt(9)
	v_add_u32_e32 v18, v18, v6
	s_waitcnt vmcnt(8)
	v_add_u32_e32 v18, v18, v7
	s_waitcnt vmcnt(7)
	v_add_u32_e32 v18, v18, v8
	s_waitcnt vmcnt(6)
	v_add_u32_e32 v18, v18, v9
	s_waitcnt vmcnt(5)
	v_add_u32_e32 v18, v18, v10
	s_waitcnt vmcnt(4)
	v_add_u32_e32 v18, v18, v11
	s_waitcnt vmcnt(3)
	v_add_u32_e32 v18, v18, v12
	s_waitcnt vmcnt(2)
	v_add_u32_e32 v18, v18, v13
	s_waitcnt vmcnt(1)
	v_add_u32_e32 v18, v18, v14
	s_waitcnt vmcnt(0)
	v_add_u32_e32 v18, v18, v15
	v_cmp_eq_u32_e32 vcc, s33, v18
	s_cbranch_vccnz .LBB0_1216
	s_and_b32 s38, s44, 0xff
	s_cmp_eq_u32 s38, 0
	s_mov_b64 s[38:39], -1
	s_mov_b64 s[42:43], -1
	s_sleep 6
	s_cbranch_scc1 .LBB0_1221
	s_and_b64 vcc, exec, s[42:43]
	s_cbranch_vccz .LBB0_1216

.LBB0_1235:
	s_and_b32 s18, s22, 0xff
	s_mov_b64 s[16:17], -1
	s_cmp_lg_u32 s18, 0
	s_mov_b64 s[20:21], -1
	s_sleep 6
	s_cbranch_scc0 .LBB0_1238
	s_and_b64 vcc, exec, s[20:21]
	s_cbranch_vccz .LBB0_1234

.LBB0_1252:
	s_and_b32 s16, s22, 0xff
	s_cmp_lg_u32 s16, 0
	s_mov_b64 s[18:19], -1
	s_sleep 6
	s_cbranch_scc0 .LBB0_1255
	s_mov_b64 s[20:21], -1
	s_and_b64 vcc, exec, s[18:19]
	s_cbranch_vccz .LBB0_1251

.LBB0_1841:
	global_load_dword v16, v17, s[4:5] sc1
	global_load_dword v1, v17, s[6:7] sc1
	global_load_dword v2, v17, s[8:9] sc1
	global_load_dword v3, v17, s[12:13] sc1
	global_load_dword v4, v17, s[14:15] sc1
	global_load_dword v5, v17, s[16:17] sc1
	global_load_dword v6, v17, s[18:19] sc1
	global_load_dword v7, v17, s[20:21] sc1
	global_load_dword v8, v17, s[22:23] sc1
	global_load_dword v9, v17, s[24:25] sc1
	global_load_dword v10, v17, s[26:27] sc1
	global_load_dword v11, v17, s[28:29] sc1
	global_load_dword v12, v17, s[30:31] sc1
	global_load_dword v13, v17, s[34:35] sc1
	global_load_dword v14, v17, s[36:37] sc1
	global_load_dword v15, v17, s[38:39] sc1
	s_mov_b64 s[40:41], -1
	s_mov_b64 s[42:43], -1
	s_waitcnt vmcnt(14)
	v_add_u32_e32 v18, v1, v16
	s_waitcnt vmcnt(13)
	v_add_u32_e32 v18, v18, v2
	s_waitcnt vmcnt(12)
	v_add_u32_e32 v18, v18, v3
	s_waitcnt vmcnt(11)
	v_add_u32_e32 v18, v18, v4
	s_waitcnt vmcnt(10)
	v_add_u32_e32 v18, v18, v5
	s_waitcnt vmcnt(9)
	v_add_u32_e32 v18, v18, v6
	s_waitcnt vmcnt(8)
	v_add_u32_e32 v18, v18, v7
	s_waitcnt vmcnt(7)
	v_add_u32_e32 v18, v18, v8
	s_waitcnt vmcnt(6)
	v_add_u32_e32 v18, v18, v9
	s_waitcnt vmcnt(5)
	v_add_u32_e32 v18, v18, v10
	s_waitcnt vmcnt(4)
	v_add_u32_e32 v18, v18, v11
	s_waitcnt vmcnt(3)
	v_add_u32_e32 v18, v18, v12
	s_waitcnt vmcnt(2)
	v_add_u32_e32 v18, v18, v13
	s_waitcnt vmcnt(1)
	v_add_u32_e32 v18, v18, v14
	s_waitcnt vmcnt(0)
	v_add_u32_e32 v18, v18, v15
	v_cmp_eq_u32_e32 vcc, s33, v18
	s_cbranch_vccnz .LBB0_1840
	s_and_b32 s40, s48, 0xff
	s_cmp_eq_u32 s40, 0
	s_mov_b64 s[40:41], -1
	s_mov_b64 s[44:45], -1
	s_sleep 6
	s_cbranch_scc1 .LBB0_1845
	s_and_b64 vcc, exec, s[44:45]
	s_cbranch_vccz .LBB0_1840
